# attention tile code outside the flash loops (prologue, compressed branch, top-k, epilogues) at wave priority 1
# speedup vs baseline: 1.2566x; 1.0064x over previous
; __device__ __forceinline__ void nsa_tile(const Params& p, int qb, int bg, char* smem) {
;     int tid = threadIdx.x; asm volatile("" : "+v"(tid));
;     const int lane = tid & 63, w = tid >> 6, fr = lane & 15, fq = lane >> 4;
;     const int b = bg >> 2, g = bg & 3, t0 = qb * 32, hq = g * 4 + w;
;     const bf16_t* projA = (const bf16_t*)(p.ws + OFF_PROJA);
;     const bf16_t* projVT = (const bf16_t*)(p.ws + OFF_PROJVT);
;     float* part = (float*)(smem + 36864);
;     u64* selmask = (u64*)(smem + 69632);
;     bf16x8 qf[2][2];
;     int tpos[2];
;     float glog[2][3];
;     ...
;     const bf16_t* qbase = projA + (size_t)(b * S + t0) * LDA;
; #pragma unroll
;     for (int qt = 0; qt < 2; ++qt) {
;         tpos[qt] = t0 + qt * 16 + fr;
;         const bf16_t* qrow = qbase + (size_t)(qt * 16 + fr) * LDA;
; #pragma unroll
;         for (int ks = 0; ks < 2; ++ks) qf[qt][ks] = *(const bf16x8*)(qrow + hq * 64 + ks * 32 + fq * 8);
; #pragma unroll
;         for (int br = 0; br < 3; ++br) glog[qt][br] = __uint_as_float(((unsigned)qrow[2048 + hq * 3 + br]) << 16);
;     }
;     f32x4 outacc[2][4];
;     {
;         const bf16_t* kcg = (const bf16_t*)(p.ws + OFF_KC) + (size_t)bg * 256 * 64;
;         const int nkp0 = (qb >> 4) + 1;
;         for (int i = 0; i < nkp0; ++i) {
;             const int q = w + 4 * i, row = q * 8 + (lane >> 3), cp = lane & 7;
;             const int f = ((row >> 1) & 1) | (((row >> 3) & 1) << 1) | (((row >> 4) & 1) << 2);
;             __builtin_amdgcn_global_load_lds((const unsigned*)(kcg + row * 64 + (cp ^ f) * 8), (__attribute__((address_space(3))) unsigned*)(smem + q * 1024), 16, 0, 0);
;         }
; __global__ void __launch_bounds__(256, 2) fwd_megakernel(Params p) {
;     ...
;     for (int r = 0; r * G < 4096; ++r) {
;         const int k = (r & 1) ? (G - 1 - (int)blockIdx.x) : (int)blockIdx.x, i = r * G + k;
;         if (i < 4096) nsa_tile(p, 127 - (i >> 5), i & 31, smem);
.LBB0_340:
	s_setprio 1
	s_bitcmp0_b32 s3, 0
	v_readlane_b32 s1, v245, 0
	v_readlane_b32 s2, v245, 62
	s_cselect_b32 s1, s1, s2
	s_add_i32 s0, s1, s0
	s_cmpk_gt_i32 s0, 0xfff
	s_cbranch_scc1 .LBB0_339
	v_writelane_b32 v244, s3, 11
	s_ashr_i32 s2, s0, 5
	s_and_b32 s3, s0, 31
	v_mov_b32_e32 v76, v114
	s_bfe_u32 s1, s0, 0x30002
	s_and_b32 s0, s0, 3
	s_sub_i32 s6, 0x7f, s2
	v_writelane_b32 v244, s0, 12
	v_ashrrev_i32_e32 v80, 6, v76
	s_lshl_b32 s13, s6, 5
	v_lshl_add_u32 v0, s0, 2, v80
	v_writelane_b32 v244, s1, 13
	s_lshl_b32 s0, s1, 12
	v_writelane_b32 v244, s0, 14
	s_add_i32 s0, s0, s13
	s_waitcnt vmcnt(0)
	v_and_b32_e32 v30, 15, v76
	s_mul_hi_u32 s1, s0, 0x1100
	s_mulk_i32 s0, 0x1100
	v_readlane_b32 s4, v245, 55
	v_readlane_b32 s5, v245, 56
	s_add_u32 s0, s4, s0
	v_lshlrev_b32_e32 v2, 6, v0
	v_lshl_add_u32 v4, v0, 1, v0
	v_mul_u32_u24_e32 v0, 0x880, v30
	s_addc_u32 s1, s5, s1
	v_ashrrev_i32_e32 v3, 31, v2
	v_lshlrev_b32_e32 v0, 1, v0
	v_ashrrev_i32_e32 v5, 31, v4
	v_lshl_add_u64 v[12:13], s[0:1], 0, v[0:1]
	v_lshlrev_b64 v[88:89], 1, v[2:3]
	v_lshlrev_b64 v[16:17], 1, v[4:5]
	v_lshl_add_u64 v[2:3], v[12:13], 0, v[88:89]
	v_and_b32_e32 v0, 48, v76
	s_mov_b64 s[0:1], 0x11000
	v_lshl_add_u64 v[18:19], v[16:17], 0, s[18:19]
	v_lshl_add_u64 v[2:3], v[2:3], 0, v[0:1]
	v_lshl_add_u64 v[20:21], v[12:13], 0, s[0:1]
	global_load_dwordx4 v[4:7], v[2:3], off
	global_load_dwordx4 v[8:11], v[2:3], off offset:64
	v_lshl_add_u64 v[2:3], v[12:13], 0, v[18:19]
	v_lshl_add_u64 v[12:13], v[20:21], 0, v[88:89]
	v_lshl_add_u64 v[16:17], v[20:21], 0, v[16:17]
	s_movk_i32 s0, 0x1000
	v_lshl_add_u64 v[22:23], v[12:13], 0, v[0:1]
	global_load_dword v120, v[2:3], off
	global_load_ushort v91, v[2:3], off offset:4
	global_load_dwordx4 v[12:15], v[22:23], off
	v_lshl_add_u64 v[2:3], v[20:21], 0, v[18:19]
	v_add_co_u32_e32 v20, vcc, s0, v16
	s_lshl_b32 s16, s3, 15
	s_nop 0
	v_addc_co_u32_e32 v21, vcc, 0, v17, vcc
	global_load_dwordx4 v[16:19], v[22:23], off offset:64
	global_load_ushort v82, v[2:3], off
	global_load_dword v111, v[20:21], off offset:2
	v_readlane_b32 s1, v245, 63
	v_lshlrev_b32_e32 v3, 1, v80
	s_add_u32 s4, s1, s16
	v_readlane_b32 s1, v244, 0
	v_and_b32_e32 v0, 7, v76
	v_bfe_u32 v2, v76, 4, 1
	v_and_b32_e32 v3, 6, v3
	s_addc_u32 s5, s1, 0
	s_lshr_b32 s3, s6, 4
	v_bitop3_b32 v0, v3, v0, v2 bitop3:0x36
	v_lshlrev_b32_e32 v20, 3, v76
	v_lshlrev_b32_e32 v0, 4, v0
	s_add_i32 s8, s3, 1
	s_mov_b32 s0, 0
	v_and_b32_e32 v22, 0x1c0, v20
	s_cmpk_lt_u32 s6, 0x70
	v_lshl_add_u64 v[2:3], s[4:5], 0, v[0:1]
	v_writelane_b32 v244, s6, 15
	s_cbranch_scc1 .LBB0_344
	v_lshl_or_b32 v20, v80, 9, v22
	s_and_b32 s0, s8, 0x1ffffff8
	v_lshl_add_u32 v0, v80, 10, v87
	v_add_u32_e32 v20, 0x3800, v20
	s_mov_b32 s1, 0

; __device__ __forceinline__ unsigned cvt_pk_bf16(float lo, float hi) { const f32x2_t f = {lo, hi}; return __builtin_bit_cast(unsigned, __builtin_convertvector(f, bf16x2_t)); }
; __device__ __forceinline__ f32x4 mfma16(bf16x8 a, bf16x8 b, f32x4 c) { return __builtin_amdgcn_mfma_f32_16x16x32_bf16(a, b, c, 0, 0, 0); }
; template <int KW, int VD, bool SEL> ...
;     ...
;                 for (int jj = 0; jj < 4; ++jj) { s[qt][tt][jj] = __builtin_amdgcn_exp2f(s[qt][tt][jj]); ps += s[qt][tt][jj]; }
;             lrow[qt] += ps;
; #pragma unroll
;             for (int i = 0; i < 2; ++i) {
;                 u32x4 pk;
;                 pk.x = cvt_pk_bf16(s[qt][2 * i][0], s[qt][2 * i][1]); pk.y = cvt_pk_bf16(s[qt][2 * i][2], s[qt][2 * i][3]);
;                 pk.z = cvt_pk_bf16(s[qt][2 * i + 1][0], s[qt][2 * i + 1][1]); pk.w = cvt_pk_bf16(s[qt][2 * i + 1][2], s[qt][2 * i + 1][3]);
;                 pf[qt][i] = __builtin_bit_cast(bf16x8, pk);
;             }
;         }
; #pragma unroll
;         for (int i = 0; i < 2; ++i) {
; #pragma unroll
;             for (int dt = 0; dt < VD / 16; ++dt) {
;                 const bf16x8 vf = *(const bf16x8*)(sV + (dt * 16 + fr) * 128 + ((i * 4 + fq) ^ vswz) * 16);
;                 O[0][dt] = mfma16(vf, pf[0][i], O[0][dt]);
;                 O[1][dt] = mfma16(vf, pf[1][i], O[1][dt]);
;             }
;         }
;         asm volatile("s_waitcnt vmcnt(0)" ::: "memory");
;         __syncthreads();
;         if (jn < 0) break;
;         j = jn; cur ^= 1;
;     }
;     ...
; #pragma unroll
;     for (int qt = 0; qt < 2; ++qt) { lrow[qt] += __shfl_xor(lrow[qt], 16); lrow[qt] += __shfl_xor(lrow[qt], 32); }
.LBB0_385:
	v_exp_f32_e32 v2, v80
	v_exp_f32_e32 v3, v81
	v_exp_f32_e32 v80, v82
	v_exp_f32_e32 v81, v83
	v_add_f32_e32 v82, 0, v2
	v_exp_f32_e32 v72, v72
	v_add_f32_e32 v82, v3, v82
	v_exp_f32_e32 v73, v73
	v_add_f32_e32 v82, v80, v82
	v_exp_f32_e32 v74, v74
	v_add_f32_e32 v82, v81, v82
	v_exp_f32_e32 v75, v75
	v_add_f32_e32 v82, v72, v82
	v_exp_f32_e32 v76, v76
	v_add_f32_e32 v82, v73, v82
	v_exp_f32_e32 v77, v77
	v_add_f32_e32 v82, v74, v82
	v_exp_f32_e32 v78, v78
	v_add_f32_e32 v82, v75, v82
	v_exp_f32_e32 v79, v79
	v_add_f32_e32 v82, v76, v82
	v_exp_f32_e32 v83, v68
	v_exp_f32_e32 v106, v69
	v_cvt_pk_bf16_f32 v69, v80, v81
	v_add_u32_e32 v80, s12, v128
	v_add_f32_e32 v82, v77, v82
	v_add_u32_e32 v81, v80, v125
	v_add_f32_e32 v82, v78, v82
	v_exp_f32_e32 v107, v70
	v_exp_f32_e32 v131, v71
	v_cvt_pk_bf16_f32 v70, v72, v73
	v_cvt_pk_bf16_f32 v71, v74, v75
	ds_read_b128 v[72:75], v81 offset:8192
	v_add_f32_e32 v68, v79, v82
	v_add_f32_e32 v68, v83, v68
	v_exp_f32_e32 v143, v60
	v_exp_f32_e32 v144, v61
	v_exp_f32_e32 v145, v62
	v_exp_f32_e32 v162, v63
	ds_read_b128 v[60:63], v81 offset:10240
	v_add_f32_e32 v68, v106, v68
	v_add_f32_e32 v82, v107, v68
	v_cvt_pk_bf16_f32 v68, v2, v3
	v_exp_f32_e32 v2, v56
	v_exp_f32_e32 v3, v57
	v_exp_f32_e32 v141, v58
	v_exp_f32_e32 v142, v59
	v_cvt_pk_bf16_f32 v58, v143, v144
	v_cvt_pk_bf16_f32 v56, v2, v3
	v_cvt_pk_bf16_f32 v59, v145, v162
	v_cvt_pk_bf16_f32 v57, v141, v142
	s_waitcnt lgkmcnt(1)
	s_setprio 2
	v_mfma_f32_16x16x32_bf16 v[48:51], v[72:75], v[68:71], v[48:51]
	v_cvt_pk_bf16_f32 v76, v76, v77
	v_cvt_pk_bf16_f32 v77, v78, v79
	v_cvt_pk_bf16_f32 v78, v83, v106
	v_mfma_f32_16x16x32_bf16 v[32:35], v[72:75], v[56:59], v[32:35]
	v_add_f32_e32 v72, v131, v82
	v_add_f32_e32 v105, v105, v72
	ds_read_b128 v[72:75], v81 offset:12288
	s_waitcnt lgkmcnt(1)
	v_mfma_f32_16x16x32_bf16 v[44:47], v[60:63], v[68:71], v[44:47]
	v_exp_f32_e32 v82, v53
	v_exp_f32_e32 v83, v54
	v_exp_f32_e32 v64, v64
	v_mfma_f32_16x16x32_bf16 v[28:31], v[60:63], v[56:59], v[28:31]
	ds_read_b128 v[60:63], v81 offset:14336
	v_exp_f32_e32 v81, v52
	v_exp_f32_e32 v65, v65
	s_waitcnt lgkmcnt(1)
	v_mfma_f32_16x16x32_bf16 v[40:43], v[72:75], v[68:71], v[40:43]
	v_exp_f32_e32 v66, v66
	v_exp_f32_e32 v67, v67
	v_add_f32_e32 v2, 0, v2
	v_mfma_f32_16x16x32_bf16 v[24:27], v[72:75], v[56:59], v[24:27]
	v_add_u32_e32 v73, v80, v126
	v_exp_f32_e32 v72, v55
	ds_read_b128 v[52:55], v73 offset:8192
	s_waitcnt lgkmcnt(1)
	v_mfma_f32_16x16x32_bf16 v[36:39], v[60:63], v[68:71], v[36:39]
	v_add_f32_e32 v2, v3, v2
	v_add_f32_e32 v2, v141, v2
	v_cvt_pk_bf16_f32 v79, v107, v131
	v_mfma_f32_16x16x32_bf16 v[20:23], v[60:63], v[56:59], v[20:23]
	ds_read_b128 v[60:63], v73 offset:10240
	v_cvt_pk_bf16_f32 v56, v81, v82
	v_cvt_pk_bf16_f32 v57, v83, v72
	v_cvt_pk_bf16_f32 v58, v64, v65
	v_cvt_pk_bf16_f32 v59, v66, v67
	v_add_f32_e32 v2, v142, v2
	s_waitcnt lgkmcnt(1)
	v_mfma_f32_16x16x32_bf16 v[48:51], v[52:55], v[76:79], v[48:51]
	v_add_f32_e32 v2, v143, v2
	v_add_f32_e32 v2, v144, v2
	v_add_f32_e32 v2, v145, v2
	v_mfma_f32_16x16x32_bf16 v[32:35], v[52:55], v[56:59], v[32:35]
	ds_read_b128 v[52:55], v73 offset:12288
	v_add_f32_e32 v2, v162, v2
	v_add_f32_e32 v2, v81, v2
	s_waitcnt lgkmcnt(1)
	v_mfma_f32_16x16x32_bf16 v[44:47], v[60:63], v[76:79], v[44:47]
	v_add_f32_e32 v2, v82, v2
	v_add_f32_e32 v2, v83, v2
	v_add_f32_e32 v2, v72, v2
	v_mfma_f32_16x16x32_bf16 v[28:31], v[60:63], v[56:59], v[28:31]
	ds_read_b128 v[60:63], v73 offset:14336
	v_add_f32_e32 v2, v64, v2
	v_add_f32_e32 v2, v65, v2
	s_waitcnt lgkmcnt(1)
	v_mfma_f32_16x16x32_bf16 v[40:43], v[52:55], v[76:79], v[40:43]
	v_add_f32_e32 v2, v66, v2
	s_waitcnt vmcnt(0)
	v_add_f32_e32 v2, v67, v2
	v_mfma_f32_16x16x32_bf16 v[24:27], v[52:55], v[56:59], v[24:27]
	s_xor_b32 s10, s10, 1
	v_add_f32_e32 v104, v104, v2
	s_cmp_gt_i32 s11, -1
	s_waitcnt lgkmcnt(0)
	v_mfma_f32_16x16x32_bf16 v[36:39], v[60:63], v[76:79], v[36:39]
	s_barrier
	v_mfma_f32_16x16x32_bf16 v[20:23], v[60:63], v[56:59], v[20:23]
	s_setprio 0
	s_cbranch_scc1 .LBB0_369
	s_setprio 1
	ds_bpermute_b32 v3, v119, v105
	ds_bpermute_b32 v2, v119, v104
	s_waitcnt lgkmcnt(0)
	v_pk_add_f32 v[2:3], v[104:105], v[2:3]
	ds_bpermute_b32 v53, v118, v3
	ds_bpermute_b32 v52, v118, v2
	s_waitcnt lgkmcnt(0)
	v_pk_add_f32 v[2:3], v[2:3], v[52:53]
	s_branch .LBB0_388

; __device__ __forceinline__ unsigned cvt_pk_bf16(float lo, float hi) { const f32x2_t f = {lo, hi}; return __builtin_bit_cast(unsigned, __builtin_convertvector(f, bf16x2_t)); }
; __device__ __forceinline__ f32x4 mfma16(bf16x8 a, bf16x8 b, f32x4 c) { return __builtin_amdgcn_mfma_f32_16x16x32_bf16(a, b, c, 0, 0, 0); }
; template <int KW, int VD, bool SEL> ...
;     ...
;                 for (int jj = 0; jj < 4; ++jj) { s[qt][tt][jj] = __builtin_amdgcn_exp2f(s[qt][tt][jj]); ps += s[qt][tt][jj]; }
;             lrow[qt] += ps;
; #pragma unroll
;             for (int i = 0; i < 2; ++i) {
;                 u32x4 pk;
;                 pk.x = cvt_pk_bf16(s[qt][2 * i][0], s[qt][2 * i][1]); pk.y = cvt_pk_bf16(s[qt][2 * i][2], s[qt][2 * i][3]);
;                 pk.z = cvt_pk_bf16(s[qt][2 * i + 1][0], s[qt][2 * i + 1][1]); pk.w = cvt_pk_bf16(s[qt][2 * i + 1][2], s[qt][2 * i + 1][3]);
;                 pf[qt][i] = __builtin_bit_cast(bf16x8, pk);
;             }
;         }
; #pragma unroll
;         for (int i = 0; i < 2; ++i) {
; #pragma unroll
;             for (int dt = 0; dt < VD / 16; ++dt) {
;                 const bf16x8 vf = *(const bf16x8*)(sV + (dt * 16 + fr) * 128 + ((i * 4 + fq) ^ vswz) * 16);
;                 O[0][dt] = mfma16(vf, pf[0][i], O[0][dt]);
;                 O[1][dt] = mfma16(vf, pf[1][i], O[1][dt]);
;             }
;         }
;         asm volatile("s_waitcnt vmcnt(0)" ::: "memory");
;         __syncthreads();
;         if (jn < 0) break;
;         j = jn; cur ^= 1;
;     }
;     ...
; #pragma unroll
;     for (int qt = 0; qt < 2; ++qt) { lrow[qt] += __shfl_xor(lrow[qt], 16); lrow[qt] += __shfl_xor(lrow[qt], 32); }
.LBB0_406:
	v_exp_f32_e32 v2, v80
	v_exp_f32_e32 v3, v81
	v_exp_f32_e32 v80, v82
	v_exp_f32_e32 v81, v83
	v_add_f32_e32 v82, 0, v2
	v_exp_f32_e32 v83, v68
	v_add_f32_e32 v82, v3, v82
	v_exp_f32_e32 v129, v69
	v_add_f32_e32 v82, v80, v82
	v_exp_f32_e32 v130, v70
	v_add_f32_e32 v68, v81, v82
	v_exp_f32_e32 v71, v71
	v_add_f32_e32 v68, v83, v68
	v_exp_f32_e32 v82, v72
	v_add_f32_e32 v68, v129, v68
	v_exp_f32_e32 v131, v73
	v_add_f32_e32 v68, v130, v68
	v_exp_f32_e32 v141, v74
	v_add_f32_e32 v68, v71, v68
	v_exp_f32_e32 v142, v75
	v_add_f32_e32 v68, v82, v68
	v_exp_f32_e32 v143, v76
	v_cvt_pk_bf16_f32 v69, v80, v81
	v_add_u32_e32 v80, s13, v126
	v_add_f32_e32 v68, v131, v68
	v_exp_f32_e32 v144, v77
	v_add_u32_e32 v81, v80, v123
	v_add_f32_e32 v68, v141, v68
	v_exp_f32_e32 v145, v78
	ds_read_b128 v[72:75], v81 offset:8192
	v_add_f32_e32 v68, v142, v68
	v_add_f32_e32 v68, v143, v68
	v_cvt_pk_bf16_f32 v71, v130, v71
	v_exp_f32_e32 v130, v60
	v_exp_f32_e32 v162, v61
	v_exp_f32_e32 v163, v62
	v_exp_f32_e32 v164, v63
	ds_read_b128 v[60:63], v81 offset:10240
	v_add_f32_e32 v68, v144, v68
	v_add_f32_e32 v76, v145, v68
	v_cvt_pk_bf16_f32 v68, v2, v3
	v_cvt_pk_bf16_f32 v70, v83, v129
	v_exp_f32_e32 v2, v56
	v_exp_f32_e32 v3, v57
	v_exp_f32_e32 v83, v58
	v_exp_f32_e32 v129, v59
	v_exp_f32_e32 v79, v79
	v_cvt_pk_bf16_f32 v56, v2, v3
	v_cvt_pk_bf16_f32 v58, v130, v162
	v_cvt_pk_bf16_f32 v57, v83, v129
	v_cvt_pk_bf16_f32 v59, v163, v164
	s_waitcnt lgkmcnt(1)
	s_setprio 2
	v_mfma_f32_16x16x32_bf16 v[48:51], v[72:75], v[68:71], v[48:51]
	v_exp_f32_e32 v64, v64
	v_exp_f32_e32 v65, v65
	v_exp_f32_e32 v66, v66
	v_mfma_f32_16x16x32_bf16 v[32:35], v[72:75], v[56:59], v[32:35]
	v_add_f32_e32 v72, v79, v76
	v_add_f32_e32 v105, v105, v72
	ds_read_b128 v[72:75], v81 offset:12288
	s_waitcnt lgkmcnt(1)
	v_mfma_f32_16x16x32_bf16 v[44:47], v[60:63], v[68:71], v[44:47]
	v_cvt_pk_bf16_f32 v76, v82, v131
	v_exp_f32_e32 v82, v53
	v_exp_f32_e32 v131, v54
	v_mfma_f32_16x16x32_bf16 v[28:31], v[60:63], v[56:59], v[28:31]
	ds_read_b128 v[60:63], v81 offset:14336
	v_exp_f32_e32 v81, v52
	v_exp_f32_e32 v67, v67
	s_waitcnt lgkmcnt(1)
	v_mfma_f32_16x16x32_bf16 v[40:43], v[72:75], v[68:71], v[40:43]
	v_add_f32_e32 v2, 0, v2
	v_add_f32_e32 v2, v3, v2
	v_add_f32_e32 v2, v83, v2
	v_mfma_f32_16x16x32_bf16 v[24:27], v[72:75], v[56:59], v[24:27]
	v_add_u32_e32 v73, v80, v124
	v_exp_f32_e32 v72, v55
	ds_read_b128 v[52:55], v73 offset:8192
	s_waitcnt lgkmcnt(1)
	v_mfma_f32_16x16x32_bf16 v[36:39], v[60:63], v[68:71], v[36:39]
	v_cvt_pk_bf16_f32 v77, v141, v142
	v_cvt_pk_bf16_f32 v78, v143, v144
	v_cvt_pk_bf16_f32 v79, v145, v79
	v_mfma_f32_16x16x32_bf16 v[20:23], v[60:63], v[56:59], v[20:23]
	ds_read_b128 v[60:63], v73 offset:10240
	v_cvt_pk_bf16_f32 v56, v81, v82
	v_cvt_pk_bf16_f32 v57, v131, v72
	v_cvt_pk_bf16_f32 v58, v64, v65
	v_cvt_pk_bf16_f32 v59, v66, v67
	v_add_f32_e32 v2, v129, v2
	s_waitcnt lgkmcnt(1)
	v_mfma_f32_16x16x32_bf16 v[48:51], v[52:55], v[76:79], v[48:51]
	v_add_f32_e32 v2, v130, v2
	v_add_f32_e32 v2, v162, v2
	v_add_f32_e32 v2, v163, v2
	v_mfma_f32_16x16x32_bf16 v[32:35], v[52:55], v[56:59], v[32:35]
	ds_read_b128 v[52:55], v73 offset:12288
	v_add_f32_e32 v2, v164, v2
	v_add_f32_e32 v2, v81, v2
	s_waitcnt lgkmcnt(1)
	v_mfma_f32_16x16x32_bf16 v[44:47], v[60:63], v[76:79], v[44:47]
	v_add_f32_e32 v2, v82, v2
	v_add_f32_e32 v2, v131, v2
	v_add_f32_e32 v2, v72, v2
	v_mfma_f32_16x16x32_bf16 v[28:31], v[60:63], v[56:59], v[28:31]
	ds_read_b128 v[60:63], v73 offset:14336
	v_add_f32_e32 v2, v64, v2
	v_add_f32_e32 v2, v65, v2
	s_waitcnt lgkmcnt(1)
	v_mfma_f32_16x16x32_bf16 v[40:43], v[52:55], v[76:79], v[40:43]
	v_add_f32_e32 v2, v66, v2
	s_waitcnt vmcnt(0)
	v_add_f32_e32 v2, v67, v2
	v_mfma_f32_16x16x32_bf16 v[24:27], v[52:55], v[56:59], v[24:27]
	s_xor_b32 s11, s11, 1
	v_add_f32_e32 v104, v104, v2
	s_cmp_gt_i32 s12, -1
	s_waitcnt lgkmcnt(0)
	v_mfma_f32_16x16x32_bf16 v[36:39], v[60:63], v[76:79], v[36:39]
	s_barrier
	v_mfma_f32_16x16x32_bf16 v[20:23], v[60:63], v[56:59], v[20:23]
	s_setprio 0
	s_cbranch_scc1 .LBB0_390
	s_setprio 1
	ds_bpermute_b32 v3, v119, v105
	ds_bpermute_b32 v2, v119, v104
	s_waitcnt lgkmcnt(0)
	v_pk_add_f32 v[2:3], v[104:105], v[2:3]
	ds_bpermute_b32 v5, v118, v3
	ds_bpermute_b32 v4, v118, v2
	s_waitcnt lgkmcnt(0)
	v_pk_add_f32 v[2:3], v[2:3], v[4:5]
	s_branch .LBB0_338

; template <int KW, int VD, bool SEL> ...
;     ...
;     if (!tiles) return;
;     int koff[NKI], voff[NVI];
; #pragma unroll
;     for (int i = 0; i < NKI; ++i) {
;         const int row = (w + 4 * i) * KRPI + lane / KCPR, cp = lane % KCPR;
;         const int f = (KW == 64) ? (((row >> 1) & 1) | (((row >> 3) & 1) << 1) | (((row >> 4) & 1) << 2)) : ((row & 3) | (((row >> 3) & 3) << 2));
;         koff[i] = row * ldk + (cp ^ f) * 8;
;     }
; #pragma unroll
;     for (int i = 0; i < NVI; ++i) {
;         const int row = (w + 4 * i) * 8 + (lane >> 3), cp = lane & 7;
;         voff[i] = row * S + (cp ^ ((row >> 1) & 7)) * 8;
;     }
; __device__ __forceinline__ void diff_tile(const Params& p, int qb, int bh, float lam, char* smem) {
;     int tid = threadIdx.x; asm volatile("" : "+v"(tid));
;     const int lane = tid & 63, w = tid >> 6, fr = lane & 15, fq = lane >> 4;
;     const int b = bh >> 3, h = bh & 7, map = w >> 1, half = w & 1, tw0 = qb * 64 + half * 32;
;     const bf16_t* projA = (const bf16_t*)(p.ws + OFF_PROJA);
;     const bf16_t* projVT = (const bf16_t*)(p.ws + OFF_PROJVT);
;     bf16x8 qf[2][2];
;     int tpos[2];
; #pragma unroll
;     for (int qt = 0; qt < 2; ++qt) {
;         tpos[qt] = tw0 + qt * 16 + fr;
;         const bf16_t* qrow = projA + (size_t)(b * S + tpos[qt]) * LDA + (h * 2 + map) * 64;
; #pragma unroll
;         for (int ks = 0; ks < 2; ++ks) qf[qt][ks] = *(const bf16x8*)(qrow + ks * 32 + fq * 8);
;     }
;     f32x4 O[2][8];
; #pragma unroll
;     for (int qt = 0; qt < 2; ++qt)
; #pragma unroll
;         for (int dt = 0; dt < 8; ++dt) O[qt][dt] = zero4();
;     float mr[2] = {-1e30f, -1e30f}, lr[2] = {0.f, 0.f};
;     const int lo[2] = {-1, -1};
;     const u64 ones[2] = {~0ull, ~0ull};
;     const u64 tiles = (qb == 63) ? ~0ull : ((1ull << (qb + 1)) - 1ull);
;     flash_branch<128, 128, false>(tiles, projA + (size_t)b * S * LDA + 1024 + h * 128, LDA, projVT + ((size_t)b * 1024 + h * 128) * S, map * 64,
;                                   qf, O, mr, lr, tpos, ones, lo, qb * 64, -1, smem);
; __global__ void __launch_bounds__(256, 2) fwd_megakernel(Params p) {
;     ...
;         for (int r = 0; r * G < 4096; ++r) {
;             const int k = (r & 1) ? (G - 1 - (int)blockIdx.x) : (int)blockIdx.x, i = r * G + k;
;             if (i < 4096) diff_tile(p, 63 - (i >> 6), i & 63, lam, smem);
.LBB0_817:
	s_setprio 1
	s_bitcmp0_b32 s17, 0
	v_readlane_b32 s7, v245, 0
	v_readlane_b32 s8, v245, 62
	s_cselect_b32 s7, s7, s8
	s_add_i32 s6, s7, s6
	s_cmpk_gt_i32 s6, 0xfff
	s_cbranch_scc1 .LBB0_816
	v_mov_b32_e32 v172, v114
	s_lshl_b32 s9, s6, 7
	s_and_b32 s18, s9, 0x380
	v_and_b32_e32 v0, 15, v172
	v_ashrrev_i32_e32 v173, 7, v172
	v_lshrrev_b32_e32 v1, 1, v172
	s_and_b32 s7, s6, 0xffffffc0
	v_and_or_b32 v171, v1, 32, v0
	v_lshl_add_u32 v0, v173, 6, s18
	v_readlane_b32 s20, v245, 55
	v_bfe_u32 v170, v172, 4, 2
	s_sub_i32 s19, 0xfc0, s7
	v_ashrrev_i32_e32 v1, 31, v0
	v_readlane_b32 s21, v245, 56
	s_bfe_u32 s8, s6, 0x30003
	v_or_b32_e32 v127, s19, v171
	v_lshl_add_u64 v[0:1], v[0:1], 1, s[20:21]
	v_lshlrev_b32_e32 v124, 4, v170
	v_mov_b32_e32 v125, v119
	s_lshl_b32 s7, s8, 12
	v_lshl_add_u64 v[0:1], v[0:1], 0, v[124:125]
	v_or_b32_e32 v125, 16, v127
	v_add_u32_e32 v118, s7, v127
	v_add_u32_e32 v126, s7, v125
	v_mad_u64_u32 v[2:3], s[10:11], v118, s3, v[0:1]
	v_mad_u64_u32 v[0:1], s[10:11], v126, s3, v[0:1]
	global_load_dwordx4 v[64:67], v[2:3], off
	global_load_dwordx4 v[68:71], v[2:3], off offset:64
	global_load_dwordx4 v[72:75], v[0:1], off
	global_load_dwordx4 v[76:79], v[0:1], off offset:64
	s_ashr_i32 s7, s6, 6
	s_sub_i32 s7, 64, s7
	s_lshl_b64 s[10:11], -1, s7
	s_not_b64 s[10:11], s[10:11]
	s_cmp_gt_u32 s6, 63
	s_cselect_b32 s7, s11, -1
	s_cselect_b32 s6, s10, -1
	v_mov_b32_e32 v0, v114
	s_cmp_eq_u64 s[6:7], 0
	s_cbranch_scc1 .LBB0_838
	v_ashrrev_i32_e32 v2, 6, v0
	v_bfe_u32 v1, v0, 4, 2
	v_lshlrev_b32_e32 v3, 2, v2
	v_lshlrev_b32_e32 v6, 1, v2
	v_and_b32_e32 v4, 15, v0
	v_or_b32_e32 v5, v3, v1
	v_and_b32_e32 v6, 12, v6
	s_mul_i32 s9, s8, 0x1100000
	v_mul_lo_u32 v5, v5, s12
	v_bitop3_b32 v6, v6, v4, v1 bitop3:0x36
	s_add_u32 s9, s20, s9
	v_lshl_or_b32 v128, v6, 3, v5
	v_add_u32_e32 v5, 16, v3
	s_addc_u32 s10, s21, 0
	s_lshl_b32 s11, s18, 1
	v_or_b32_e32 v6, v5, v1
	v_lshrrev_b32_e32 v5, 1, v5
	s_add_u32 s20, s9, s11
	v_and_b32_e32 v5, 12, v5
	s_addc_u32 s21, s10, 0
	s_lshl_b32 s8, s8, 23
	v_readlane_b32 s9, v245, 57
	v_mul_lo_u32 v6, v6, s12
	v_bitop3_b32 v5, v5, v4, v1 bitop3:0x36
	v_add_u32_e32 v3, 48, v3
	s_add_u32 s8, s9, s8
	v_readlane_b32 s9, v245, 58
	v_lshl_or_b32 v130, v5, 3, v6
	v_or_b32_e32 v5, v3, v1
	v_lshrrev_b32_e32 v3, 1, v3
	s_addc_u32 s9, s9, 0
	s_lshl_b32 s10, s18, 13
	v_and_b32_e32 v3, 12, v3
	s_add_u32 s22, s8, s10
	v_mul_lo_u32 v5, v5, s12
	v_bitop3_b32 v3, v3, v4, v1 bitop3:0x36
	s_addc_u32 s23, s9, 0
	v_lshl_or_b32 v134, v3, 3, v5
	v_bfe_u32 v3, v0, 3, 3
	v_lshl_or_b32 v3, v2, 3, v3
	s_ff1_i32_b64 s10, s[6:7]
	s_add_u32 s8, s6, -1
	v_lshlrev_b32_e32 v5, 12, v3
	v_lshrrev_b32_e32 v3, 1, v3
	s_addc_u32 s9, s7, -1
	s_mul_i32 s11, s10, 0x44000
	v_xor_b32_e32 v3, v3, v0
	s_add_u32 s24, s20, s11
	v_lshlrev_b32_e32 v3, 3, v3
	v_lshlrev_b32_e32 v174, 10, v2
	s_addc_u32 s25, s21, 0
	v_ashrrev_i32_e32 v129, 31, v128
	v_and_or_b32 v136, v3, 56, v5
	v_lshl_add_u64 v[2:3], v[128:129], 1, s[24:25]
	v_readfirstlane_b32 s26, v174
	v_lshl_add_u64 v[2:3], v[2:3], 0, s[0:1]
	s_mov_b32 m0, s26
	v_ashrrev_i32_e32 v131, 31, v130
	v_add_u32_e32 v5, 0x1000, v174
	v_add_u32_e32 v132, 0x11000, v128
	global_load_lds_dwordx4 v[2:3], off
	v_lshl_add_u64 v[2:3], v[130:131], 1, s[24:25]
	v_readfirstlane_b32 s26, v5
	v_lshl_add_u64 v[2:3], v[2:3], 0, s[0:1]
	s_mov_b32 m0, s26
	v_ashrrev_i32_e32 v133, 31, v132
	v_add_u32_e32 v5, 0x2000, v174
	global_load_lds_dwordx4 v[2:3], off
	v_lshl_add_u64 v[2:3], v[132:133], 1, s[24:25]
	v_readfirstlane_b32 s26, v5
	v_lshl_add_u64 v[2:3], v[2:3], 0, s[0:1]
	s_mov_b32 m0, s26
	v_ashrrev_i32_e32 v135, 31, v134
	v_add_u32_e32 v5, 0x3000, v174
	s_lshl_b32 s11, s10, 7
	global_load_lds_dwordx4 v[2:3], off
	v_lshl_add_u64 v[2:3], v[134:135], 1, s[24:25]
	v_readfirstlane_b32 s24, v5
	s_mov_b32 m0, s24
	s_add_u32 s24, s22, s11
	v_add_u32_e32 v5, 0x4000, v174
	v_add_u32_e32 v138, 0x20000, v136
	v_lshl_add_u64 v[2:3], v[2:3], 0, s[0:1]
	s_addc_u32 s25, s23, 0
	v_ashrrev_i32_e32 v137, 31, v136
	v_readfirstlane_b32 s11, v5
	v_add_u32_e32 v5, 0x5000, v174
	v_add_u32_e32 v140, 0x40000, v136
	global_load_lds_dwordx4 v[2:3], off
	v_lshl_add_u64 v[2:3], v[136:137], 1, s[24:25]
	s_mov_b32 m0, s11
	v_ashrrev_i32_e32 v139, 31, v138
	v_readfirstlane_b32 s11, v5
	v_add_u32_e32 v5, 0x6000, v174
	v_add_u32_e32 v142, 0x60000, v136
	global_load_lds_dwordx4 v[2:3], off
	v_lshl_add_u64 v[2:3], v[138:139], 1, s[24:25]
	s_mov_b32 m0, s11
	v_ashrrev_i32_e32 v141, 31, v140
	v_readfirstlane_b32 s11, v5
	v_add_u32_e32 v5, 0x7000, v174
	global_load_lds_dwordx4 v[2:3], off
	v_lshl_add_u64 v[2:3], v[140:141], 1, s[24:25]
	s_mov_b32 m0, s11
	v_ashrrev_i32_e32 v143, 31, v142
	v_readfirstlane_b32 s11, v5
	global_load_lds_dwordx4 v[2:3], off
	v_lshl_add_u64 v[2:3], v[142:143], 1, s[24:25]
	s_mov_b32 m0, s11
	v_lshlrev_b32_e32 v5, 1, v0
	global_load_lds_dwordx4 v[2:3], off
	v_lshrrev_b32_e32 v2, 1, v0
	v_bfe_u32 v3, v0, 1, 3
	v_and_b32_e32 v0, 3, v0
	v_and_or_b32 v0, v5, 24, v0
	v_lshlrev_b32_e32 v5, 3, v173
	v_or_b32_e32 v6, v1, v5
	v_bitop3_b32 v5, v1, v4, v5 bitop3:0x36
	v_lshlrev_b32_e32 v179, 8, v0
	v_bitop3_b32 v0, v1, v2, 7 bitop3:0x78
	s_waitcnt vmcnt(0)
	v_lshlrev_b32_e32 v175, 4, v5
	v_bitop3_b32 v5, v6, v4, 4 bitop3:0x36
	v_lshlrev_b32_e32 v180, 4, v0
	v_bitop3_b32 v0, v1, v3, 4 bitop3:0x36
	v_mov_b32_e32 v8, v119
	v_mov_b32_e32 v9, v119
	v_mov_b32_e32 v10, v119
	v_mov_b32_e32 v11, v119
	v_lshlrev_b32_e32 v176, 4, v5
	v_lshlrev_b32_e32 v177, 3, v1
	v_lshlrev_b32_e32 v178, 7, v4
	v_lshlrev_b32_e32 v181, 4, v0
	v_mov_b64_e32 v[14:15], v[10:11]
	v_mov_b64_e32 v[18:19], v[10:11]
	v_mov_b64_e32 v[22:23], v[10:11]
	v_mov_b64_e32 v[26:27], v[10:11]
	v_mov_b64_e32 v[30:31], v[10:11]
	v_mov_b64_e32 v[34:35], v[10:11]
	v_mov_b64_e32 v[38:39], v[10:11]
	v_mov_b64_e32 v[42:43], v[10:11]
	v_mov_b64_e32 v[46:47], v[10:11]
	v_mov_b64_e32 v[50:51], v[10:11]
	v_mov_b64_e32 v[54:55], v[10:11]
	v_mov_b64_e32 v[58:59], v[10:11]
	v_mov_b64_e32 v[62:63], v[10:11]
	v_mov_b64_e32 v[4:5], v[8:9]
	v_mov_b64_e32 v[0:1], v[8:9]
	s_and_b64 s[6:7], s[8:9], s[6:7]
	s_mov_b32 s24, 0
	v_mov_b32_e32 v182, 0xf149f2ca
	v_mov_b32_e32 v144, 0
	v_mov_b64_e32 v[12:13], v[8:9]
	v_mov_b64_e32 v[16:17], v[8:9]
	v_mov_b64_e32 v[20:21], v[8:9]
	v_mov_b64_e32 v[24:25], v[8:9]
	v_mov_b64_e32 v[28:29], v[8:9]
	v_mov_b64_e32 v[32:33], v[8:9]
	v_mov_b64_e32 v[36:37], v[8:9]
	v_mov_b64_e32 v[40:41], v[8:9]
	v_mov_b64_e32 v[44:45], v[8:9]
	v_mov_b64_e32 v[48:49], v[8:9]
	v_mov_b64_e32 v[52:53], v[8:9]
	v_mov_b64_e32 v[56:57], v[8:9]
	v_mov_b64_e32 v[60:61], v[8:9]
	v_mov_b64_e32 v[6:7], v[10:11]
	v_mov_b64_e32 v[2:3], v[10:11]
	v_mov_b32_e32 v145, 0
	v_mov_b32_e32 v183, 0xf149f2ca
	v_lshlrev_b32_e32 v246, 1, v128
	v_lshlrev_b32_e32 v247, 1, v130
	v_lshlrev_b32_e32 v248, 1, v132
	v_lshlrev_b32_e32 v249, 1, v134
	v_lshlrev_b32_e32 v250, 1, v136
	v_lshlrev_b32_e32 v251, 1, v138
	v_lshlrev_b32_e32 v252, 1, v140
	v_lshlrev_b32_e32 v253, 1, v142
	s_waitcnt vmcnt(0) lgkmcnt(0)
	s_barrier
	s_cmp_lg_u64 s[6:7], 0
	s_cbranch_scc1 .LBB0_822
	s_branch .LBB0_821

; __device__ __forceinline__ unsigned cvt_pk_bf16(float lo, float hi) { const f32x2_t f = {lo, hi}; return __builtin_bit_cast(unsigned, __builtin_convertvector(f, bf16x2_t)); }
; __device__ __forceinline__ f32x4 mfma16(bf16x8 a, bf16x8 b, f32x4 c) { return __builtin_amdgcn_mfma_f32_16x16x32_bf16(a, b, c, 0, 0, 0); }
; template <int KW, int VD, bool SEL> ...
;     ...
;                 for (int jj = 0; jj < 4; ++jj) { s[qt][tt][jj] = __builtin_amdgcn_exp2f(s[qt][tt][jj]); ps += s[qt][tt][jj]; }
;             lrow[qt] += ps;
; #pragma unroll
;             for (int i = 0; i < 2; ++i) {
;                 u32x4 pk;
;                 pk.x = cvt_pk_bf16(s[qt][2 * i][0], s[qt][2 * i][1]); pk.y = cvt_pk_bf16(s[qt][2 * i][2], s[qt][2 * i][3]);
;                 pk.z = cvt_pk_bf16(s[qt][2 * i + 1][0], s[qt][2 * i + 1][1]); pk.w = cvt_pk_bf16(s[qt][2 * i + 1][2], s[qt][2 * i + 1][3]);
;                 pf[qt][i] = __builtin_bit_cast(bf16x8, pk);
;             }
;         }
; #pragma unroll
;         for (int i = 0; i < 2; ++i) {
; #pragma unroll
;             for (int dt = 0; dt < VD / 16; ++dt) {
;                 const bf16x8 vf = *(const bf16x8*)(sV + (dt * 16 + fr) * 128 + ((i * 4 + fq) ^ vswz) * 16);
;                 O[0][dt] = mfma16(vf, pf[0][i], O[0][dt]);
;                 O[1][dt] = mfma16(vf, pf[1][i], O[1][dt]);
;             }
;         }
;         asm volatile("s_waitcnt vmcnt(0)" ::: "memory");
;         __syncthreads();
;         if (jn < 0) break;
;         j = jn; cur ^= 1;
;     }
;     ...
; #pragma unroll
;     for (int qt = 0; qt < 2; ++qt) { lrow[qt] += __shfl_xor(lrow[qt], 16); lrow[qt] += __shfl_xor(lrow[qt], 32); }
.LBB0_836:
	v_add_u32_e32 v194, s26, v178
	v_add_u32_e32 v195, v194, v180
	v_exp_f32_e32 v184, v108
	v_exp_f32_e32 v185, v109
	v_exp_f32_e32 v186, v110
	v_exp_f32_e32 v187, v111
	ds_read_b128 v[108:111], v195 offset:16384
	v_exp_f32_e32 v198, v100
	v_exp_f32_e32 v199, v101
	v_exp_f32_e32 v200, v102
	v_exp_f32_e32 v201, v103
	ds_read_b128 v[100:103], v195 offset:18432
	v_exp_f32_e32 v188, v104
	v_exp_f32_e32 v189, v105
	v_exp_f32_e32 v190, v106
	v_exp_f32_e32 v191, v107
	v_exp_f32_e32 v192, v96
	v_exp_f32_e32 v193, v97
	v_exp_f32_e32 v196, v98
	v_exp_f32_e32 v197, v99
	v_cvt_pk_bf16_f32 v104, v184, v185
	v_cvt_pk_bf16_f32 v105, v186, v187
	v_cvt_pk_bf16_f32 v106, v188, v189
	v_cvt_pk_bf16_f32 v107, v190, v191
	v_cvt_pk_bf16_f32 v96, v192, v193
	v_cvt_pk_bf16_f32 v97, v196, v197
	v_cvt_pk_bf16_f32 v98, v198, v199
	v_cvt_pk_bf16_f32 v99, v200, v201
	s_waitcnt lgkmcnt(1)
	s_setprio 2
	v_mfma_f32_16x16x32_bf16 v[60:63], v[108:111], v[104:107], v[60:63]
	v_exp_f32_e32 v202, v92
	v_exp_f32_e32 v203, v93
	v_exp_f32_e32 v204, v94
	v_mfma_f32_16x16x32_bf16 v[28:31], v[108:111], v[96:99], v[28:31]
	v_exp_f32_e32 v205, v95
	v_add_u32_e32 v194, v194, v181
	v_exp_f32_e32 v206, v88
	s_waitcnt lgkmcnt(0)
	v_mfma_f32_16x16x32_bf16 v[56:59], v[100:103], v[104:107], v[56:59]
	v_exp_f32_e32 v207, v89
	v_exp_f32_e32 v208, v90
	v_exp_f32_e32 v209, v91
	v_mfma_f32_16x16x32_bf16 v[24:27], v[100:103], v[96:99], v[24:27]
	ds_read_b128 v[100:103], v195 offset:20480
	ds_read_b128 v[108:111], v195 offset:22528
	ds_read_b128 v[92:95], v195 offset:28672
	v_cvt_pk_bf16_f32 v88, v202, v203
	s_waitcnt lgkmcnt(2)
	v_mfma_f32_16x16x32_bf16 v[52:55], v[100:103], v[104:107], v[52:55]
	v_cvt_pk_bf16_f32 v89, v204, v205
	v_cvt_pk_bf16_f32 v90, v206, v207
	v_cvt_pk_bf16_f32 v91, v208, v209
	v_mfma_f32_16x16x32_bf16 v[20:23], v[100:103], v[96:99], v[20:23]
	ds_read_b128 v[100:103], v195 offset:24576
	s_xor_b32 s24, s24, 1
	s_cmp_gt_i32 s25, -1
	s_waitcnt lgkmcnt(2)
	v_mfma_f32_16x16x32_bf16 v[48:51], v[108:111], v[104:107], v[48:51]
	v_mfma_f32_16x16x32_bf16 v[16:19], v[108:111], v[96:99], v[16:19]
	ds_read_b128 v[108:111], v195 offset:26624
	s_waitcnt lgkmcnt(1)
	v_mfma_f32_16x16x32_bf16 v[44:47], v[100:103], v[104:107], v[44:47]
	v_mfma_f32_16x16x32_bf16 v[12:15], v[100:103], v[96:99], v[12:15]
	ds_read_b128 v[100:103], v195 offset:30720
	s_waitcnt lgkmcnt(1)
	v_mfma_f32_16x16x32_bf16 v[40:43], v[108:111], v[104:107], v[40:43]
	v_mfma_f32_16x16x32_bf16 v[8:11], v[108:111], v[96:99], v[8:11]
	v_exp_f32_e32 v108, v80
	v_exp_f32_e32 v109, v81
	v_exp_f32_e32 v110, v82
	v_exp_f32_e32 v111, v83
	ds_read_b128 v[80:83], v194 offset:16384
	v_mfma_f32_16x16x32_bf16 v[36:39], v[92:95], v[104:107], v[36:39]
	v_mfma_f32_16x16x32_bf16 v[4:7], v[92:95], v[96:99], v[4:7]
	ds_read_b128 v[92:95], v194 offset:18432
	s_waitcnt lgkmcnt(2)
	v_mfma_f32_16x16x32_bf16 v[32:35], v[100:103], v[104:107], v[32:35]
	v_exp_f32_e32 v104, v84
	v_exp_f32_e32 v105, v85
	v_exp_f32_e32 v106, v86
	v_mfma_f32_16x16x32_bf16 v[0:3], v[100:103], v[96:99], v[0:3]
	v_exp_f32_e32 v96, v87
	v_cvt_pk_bf16_f32 v84, v108, v109
	v_cvt_pk_bf16_f32 v85, v110, v111
	v_cvt_pk_bf16_f32 v86, v104, v105
	v_cvt_pk_bf16_f32 v87, v106, v96
	s_waitcnt lgkmcnt(1)
	v_mfma_f32_16x16x32_bf16 v[60:63], v[80:83], v[88:91], v[60:63]
	v_add_f32_e32 v97, 0, v184
	v_add_f32_e32 v97, v185, v97
	v_add_f32_e32 v97, v186, v97
	v_mfma_f32_16x16x32_bf16 v[28:31], v[80:83], v[84:87], v[28:31]
	ds_read_b128 v[80:83], v194 offset:20480
	s_waitcnt lgkmcnt(1)
	v_mfma_f32_16x16x32_bf16 v[56:59], v[92:95], v[88:91], v[56:59]
	v_mfma_f32_16x16x32_bf16 v[24:27], v[92:95], v[84:87], v[24:27]
	v_add_f32_e32 v92, v187, v97
	v_add_f32_e32 v97, v188, v92
	ds_read_b128 v[92:95], v194 offset:22528
	v_add_f32_e32 v97, v189, v97
	v_add_f32_e32 v97, v190, v97
	v_add_f32_e32 v97, v191, v97
	s_waitcnt lgkmcnt(1)
	v_mfma_f32_16x16x32_bf16 v[52:55], v[80:83], v[88:91], v[52:55]
	v_mfma_f32_16x16x32_bf16 v[20:23], v[80:83], v[84:87], v[20:23]
	v_add_f32_e32 v80, v202, v97
	v_add_f32_e32 v97, v203, v80
	ds_read_b128 v[80:83], v194 offset:24576
	v_add_f32_e32 v97, v204, v97
	v_add_f32_e32 v97, v205, v97
	v_add_f32_e32 v97, v206, v97
	s_waitcnt lgkmcnt(1)
	v_mfma_f32_16x16x32_bf16 v[48:51], v[92:95], v[88:91], v[48:51]
	v_mfma_f32_16x16x32_bf16 v[16:19], v[92:95], v[84:87], v[16:19]
	v_add_f32_e32 v92, v207, v97
	v_add_f32_e32 v97, v208, v92
	ds_read_b128 v[92:95], v194 offset:26624
	v_add_f32_e32 v97, v209, v97
	v_add_f32_e32 v145, v145, v97
	v_add_f32_e32 v97, 0, v192
	s_waitcnt lgkmcnt(1)
	v_mfma_f32_16x16x32_bf16 v[44:47], v[80:83], v[88:91], v[44:47]
	v_mfma_f32_16x16x32_bf16 v[12:15], v[80:83], v[84:87], v[12:15]
	v_add_f32_e32 v80, v193, v97
	v_add_f32_e32 v97, v196, v80
	v_add_f32_e32 v97, v197, v97
	v_add_f32_e32 v97, v198, v97
	ds_read_b128 v[80:83], v194 offset:28672
	v_add_f32_e32 v97, v199, v97
	s_waitcnt lgkmcnt(1)
	v_mfma_f32_16x16x32_bf16 v[40:43], v[92:95], v[88:91], v[40:43]
	v_mfma_f32_16x16x32_bf16 v[8:11], v[92:95], v[84:87], v[8:11]
	v_add_f32_e32 v92, v200, v97
	v_add_f32_e32 v97, v201, v92
	ds_read_b128 v[92:95], v194 offset:30720
	v_add_f32_e32 v97, v108, v97
	v_add_f32_e32 v97, v109, v97
	v_add_f32_e32 v97, v110, v97
	s_waitcnt lgkmcnt(1)
	v_mfma_f32_16x16x32_bf16 v[36:39], v[80:83], v[88:91], v[36:39]
	s_waitcnt vmcnt(0)
	s_waitcnt lgkmcnt(0)
	s_barrier
	v_mfma_f32_16x16x32_bf16 v[4:7], v[80:83], v[84:87], v[4:7]
	v_add_f32_e32 v80, v111, v97
	v_add_f32_e32 v80, v104, v80
	v_add_f32_e32 v80, v105, v80
	v_mfma_f32_16x16x32_bf16 v[32:35], v[92:95], v[88:91], v[32:35]
	v_add_f32_e32 v80, v106, v80
	v_add_f32_e32 v80, v96, v80
	v_add_f32_e32 v144, v144, v80
	v_mfma_f32_16x16x32_bf16 v[0:3], v[92:95], v[84:87], v[0:3]
	s_setprio 0
	s_cbranch_scc1 .LBB0_820
	s_setprio 1
	ds_bpermute_b32 v65, v163, v145
	ds_bpermute_b32 v64, v163, v144
	s_waitcnt lgkmcnt(0)
	v_pk_add_f32 v[64:65], v[144:145], v[64:65]
	ds_bpermute_b32 v67, v162, v65
	ds_bpermute_b32 v66, v162, v64
	s_waitcnt lgkmcnt(0)
	v_pk_add_f32 v[64:65], v[64:65], v[66:67]
	s_branch .LBB0_839
